# attention: second item takes span^8 (edge spans paired with interior spans), on stack13
# baseline (speedup 1.0000x reference)
; __device__ __forceinline__ void attn_phase(const Args& A, LAS unsigned char* lds, int tid, int lane, int wave, int bx, int G) {
;     ...
;     if (!AT_VALID(0)) return;
;     bf16x8 qf[4], kf[5][4];
;     At32 cur; AT_TASK(cur, AT_ITEM(0), 0);
;     at32_load_qk(A, cur, lane, qf, kf);
; #pragma unroll 1
;     for (int kstep = 0; AT_VALID(kstep); ++kstep) {
;         const int item = AT_ITEM(kstep), span = item & 15, bh = item >> 4, pos0 = span * 512;
; #pragma unroll 1
;         for (int i = 0; i < 6; ++i) {
;             At32 nxt;
;             if (i < 5) { AT_TASK(nxt, item, i + 1); } else { const int ni = AT_VALID(kstep + 1) ? AT_ITEM(kstep + 1) : item; AT_TASK(nxt, ni, 0); }
.LBB0_382:
	s_andn2_b64 vcc, exec, s[6:7]
	s_cbranch_vccnz .LBB0_384
	s_lshl_b32 s14, s25, 5
	v_readlane_b32 s6, v253, 62
	s_add_i32 s6, s6, s14
	s_and_b32 s6, s6, -16
	v_readlane_b32 s7, v253, 57
	s_or_b32 s2, s6, s7
	s_cmp_eq_u32 s14, 32
	s_cselect_b32 s98, 8, 0
	s_xor_b32 s2, s2, s98
.LBB0_384:
	s_lshl_b32 s6, s2, 9
	s_and_b32 s10, s6, 0x1e00
	s_ashr_i32 s24, s2, 4
	v_writelane_b32 v254, s2, 59
	s_lshr_b32 s2, s10, 4
	v_writelane_b32 v254, s2, 60
	s_lshr_b32 s6, s10, 2
	v_readlane_b32 s2, v254, 57
	s_or_b32 s2, s6, s2
	v_readlane_b32 s6, v252, 10
	v_writelane_b32 v254, s2, 61
	s_add_i32 s2, s25, 1
	v_writelane_b32 v254, s2, 62
	s_mul_i32 s20, s2, s6
	v_readlane_b32 s6, v254, 48
	s_add_i32 s2, s20, s6
	s_cmpk_lt_i32 s2, 0x200
	s_cselect_b64 s[6:7], -1, 0
	s_cmp_eq_u32 s25, 0
	v_writelane_b32 v255, s6, 0
	v_writelane_b32 v254, s2, 63
	s_mov_b32 s30, 0
	v_writelane_b32 v255, s7, 1
	s_cselect_b64 s[6:7], -1, 0
	v_writelane_b32 v255, s6, 2
	s_mov_b32 s25, 8
	s_nop 0
	v_writelane_b32 v255, s7, 3
	v_readlane_b32 s6, v253, 63
	s_add_i32 s6, s6, s14
	s_and_b32 s6, s6, -16
	v_readlane_b32 s7, v253, 57
	s_or_b32 s2, s6, s7
	s_cmp_eq_u32 s14, 0
	s_cselect_b32 s98, 8, 0
	s_xor_b32 s2, s2, s98
	v_writelane_b32 v255, s2, 4
	s_cmp_eq_u32 s30, 5
	s_mov_b64 s[6:7], -1
	s_cbranch_scc1 .LBB0_396
	s_branch .LBB0_389
